# v36: v33 + EpiUp (phases 1,8) sigmoid -log2e multiply and +1.0 add packed into v_pk_mul_f32/v_pk_add_f32 (bitwise identical)
# baseline (speedup 1.0000x reference)
.LBB0_176:
	v_mov_b32_e32 v254, 0xbfb8aa3b
	v_lshl_add_u32 v164, s14, 8, v138
	v_ashrrev_i32_e32 v165, 31, v164
	v_lshl_add_u64 v[164:165], v[164:165], 2, s[84:85]
	global_load_dword v170, v[164:165], off
	global_load_dword v175, v[164:165], off offset:64
	global_load_dword v176, v[164:165], off offset:128
	global_load_dword v177, v[164:165], off offset:192
	global_load_dword v178, v[164:165], off offset:512
	global_load_dword v179, v[164:165], off offset:576
	global_load_dword v180, v[164:165], off offset:640
	global_load_dword v181, v[164:165], off offset:704
	s_lshl_b32 s9, s15, 1
	s_mul_i32 s14, s14, 44
	s_add_i32 s14, s14, s9
	s_or_b32 s14, s14, s53
	s_ashr_i32 s15, s14, 31
	s_lshl_b64 s[14:15], s[14:15], 15
	s_add_u32 s14, s80, s14
	s_addc_u32 s15, s81, s15
	s_waitcnt vmcnt(0)
	v_fmamk_f32 v170, v170, 0x3a800000, v169
	v_cmp_gt_f32_e32 vcc, s58, v170
	v_mul_f32_e32 v171, 0x4b800000, v170
	s_nop 0
	v_cndmask_b32_e32 v170, v170, v171, vcc
	v_rsq_f32_e32 v170, v170
	s_nop 0
	v_mul_f32_e32 v171, 0x45800000, v170
	v_cndmask_b32_e32 v170, v170, v171, vcc
	v_pk_mul_f32 v[124:125], v[124:125], v[170:171] op_sel_hi:[1,0]
	s_nop 0
	v_mul_f32_e32 v171, 0xbfb8aa3b, v124
	v_exp_f32_e32 v171, v171
	s_nop 0
	v_add_f32_e32 v171, 1.0, v171
	v_rcp_f32_e32 v172, v171
	v_pk_mul_f32 v[116:117], v[116:117], v[170:171] op_sel_hi:[1,0]
	v_mul_f32_e32 v171, 0xbfb8aa3b, v125
	v_exp_f32_e32 v171, v171
	s_nop 0
	v_add_f32_e32 v171, 1.0, v171
	v_rcp_f32_e32 v173, v171
	v_pk_mul_f32 v[118:119], v[118:119], v[170:171] op_sel_hi:[1,0]
	v_pk_mul_f32 v[120:121], v[120:121], v[170:171] op_sel_hi:[1,0]
	v_pk_mul_f32 v[112:113], v[112:113], v[170:171] op_sel_hi:[1,0]
	v_pk_mul_f32 v[124:125], v[124:125], v[172:173]
	v_pk_mul_f32 v[114:115], v[114:115], v[170:171] op_sel_hi:[1,0]
	v_pk_mul_f32 v[116:117], v[116:117], v[124:125]
	v_pk_mul_f32 v[124:125], v[126:127], v[170:171] op_sel_hi:[1,0]
	s_nop 0
	v_pk_mul_f32 v[126:127], v[124:125], v[254:255] op_sel_hi:[1,0]
	s_nop 0
	v_exp_f32_e32 v126, v126
	v_exp_f32_e32 v127, v127
	s_nop 0
	v_pk_add_f32 v[126:127], v[126:127], 1.0 op_sel_hi:[1,0]
	s_nop 0
	v_rcp_f32_e32 v126, v126
	v_rcp_f32_e32 v127, v127
	s_nop 0
	v_pk_mul_f32 v[124:125], v[124:125], v[126:127]
	s_nop 0
	v_pk_mul_f32 v[118:119], v[118:119], v[124:125]
	v_pk_mul_f32 v[124:125], v[120:121], v[254:255] op_sel_hi:[1,0]
	s_nop 0
	v_exp_f32_e32 v124, v124
	v_exp_f32_e32 v125, v125
	s_nop 0
	v_pk_add_f32 v[124:125], v[124:125], 1.0 op_sel_hi:[1,0]
	s_nop 0
	v_rcp_f32_e32 v124, v124
	v_rcp_f32_e32 v125, v125
	s_nop 0
	v_pk_mul_f32 v[120:121], v[120:121], v[124:125]
	s_nop 0
	v_pk_mul_f32 v[120:121], v[112:113], v[120:121]
	v_pk_mul_f32 v[112:113], v[122:123], v[170:171] op_sel_hi:[1,0]
	s_nop 0
	v_pk_mul_f32 v[122:123], v[112:113], v[254:255] op_sel_hi:[1,0]
	s_nop 0
	v_exp_f32_e32 v122, v122
	v_exp_f32_e32 v123, v123
	s_nop 0
	v_pk_add_f32 v[122:123], v[122:123], 1.0 op_sel_hi:[1,0]
	s_nop 0
	v_rcp_f32_e32 v122, v122
	v_rcp_f32_e32 v123, v123
	s_nop 0
	v_pk_mul_f32 v[112:113], v[112:113], v[122:123]
	s_nop 0
	v_pk_mul_f32 v[122:123], v[114:115], v[112:113]
	v_cvt_pk_bf16_f32 v112, v116, v117
	v_lshl_add_u64 v[116:117], s[14:15], 0, v[140:141]
	v_cvt_pk_bf16_f32 v113, v118, v119
	v_cvt_pk_bf16_f32 v114, v120, v121
	v_cvt_pk_bf16_f32 v115, v122, v123
	v_lshl_add_u64 v[116:117], v[116:117], 0, v[136:137]
	global_store_dwordx4 v[116:117], v[112:115], off nt
	s_nop 1
	v_fmamk_f32 v112, v175, 0x3a800000, v169
	v_cmp_gt_f32_e32 vcc, s58, v112
	v_mul_f32_e32 v113, 0x4b800000, v112
	s_nop 0
	v_cndmask_b32_e32 v112, v112, v113, vcc
	v_rsq_f32_e32 v112, v112
	s_nop 0
	v_mul_f32_e32 v113, 0x45800000, v112
	v_cndmask_b32_e32 v112, v112, v113, vcc
	v_pk_mul_f32 v[108:109], v[108:109], v[112:113] op_sel_hi:[1,0]
	s_nop 0
	v_mul_f32_e32 v113, 0xbfb8aa3b, v108
	v_exp_f32_e32 v113, v113
	s_nop 0
	v_add_f32_e32 v113, 1.0, v113
	v_rcp_f32_e32 v114, v113
	v_pk_mul_f32 v[100:101], v[100:101], v[112:113] op_sel_hi:[1,0]
	v_mul_f32_e32 v113, 0xbfb8aa3b, v109
	v_exp_f32_e32 v113, v113
	s_nop 0
	v_add_f32_e32 v113, 1.0, v113
	v_rcp_f32_e32 v115, v113
	v_pk_mul_f32 v[102:103], v[102:103], v[112:113] op_sel_hi:[1,0]
	v_pk_mul_f32 v[104:105], v[104:105], v[112:113] op_sel_hi:[1,0]
	v_pk_mul_f32 v[96:97], v[96:97], v[112:113] op_sel_hi:[1,0]
	v_pk_mul_f32 v[108:109], v[108:109], v[114:115]
	v_pk_mul_f32 v[98:99], v[98:99], v[112:113] op_sel_hi:[1,0]
	v_pk_mul_f32 v[100:101], v[100:101], v[108:109]
	v_pk_mul_f32 v[108:109], v[110:111], v[112:113] op_sel_hi:[1,0]
	s_nop 0
	v_pk_mul_f32 v[110:111], v[108:109], v[254:255] op_sel_hi:[1,0]
	s_nop 0
	v_exp_f32_e32 v110, v110
	v_exp_f32_e32 v111, v111
	s_nop 0
	v_pk_add_f32 v[110:111], v[110:111], 1.0 op_sel_hi:[1,0]
	s_nop 0
	v_rcp_f32_e32 v110, v110
	v_rcp_f32_e32 v111, v111
	s_nop 0
	v_pk_mul_f32 v[108:109], v[108:109], v[110:111]
	s_nop 0
	v_pk_mul_f32 v[102:103], v[102:103], v[108:109]
	v_pk_mul_f32 v[108:109], v[104:105], v[254:255] op_sel_hi:[1,0]
	s_nop 0
	v_exp_f32_e32 v108, v108
	v_exp_f32_e32 v109, v109
	s_nop 0
	v_pk_add_f32 v[108:109], v[108:109], 1.0 op_sel_hi:[1,0]
	s_nop 0
	v_rcp_f32_e32 v108, v108
	v_rcp_f32_e32 v109, v109
	s_nop 0
	v_pk_mul_f32 v[104:105], v[104:105], v[108:109]
	s_nop 0
	v_pk_mul_f32 v[104:105], v[96:97], v[104:105]
	v_pk_mul_f32 v[96:97], v[106:107], v[112:113] op_sel_hi:[1,0]
	s_nop 0
	v_pk_mul_f32 v[106:107], v[96:97], v[254:255] op_sel_hi:[1,0]
	s_nop 0
	v_exp_f32_e32 v106, v106
	v_exp_f32_e32 v107, v107
	s_nop 0
	v_pk_add_f32 v[106:107], v[106:107], 1.0 op_sel_hi:[1,0]
	s_nop 0
	v_rcp_f32_e32 v106, v106
	v_rcp_f32_e32 v107, v107
	s_nop 0
	v_pk_mul_f32 v[96:97], v[96:97], v[106:107]
	s_nop 0
	v_pk_mul_f32 v[106:107], v[98:99], v[96:97]
	v_cvt_pk_bf16_f32 v96, v100, v101
	v_lshl_add_u64 v[100:101], s[14:15], 0, v[142:143]
	v_cvt_pk_bf16_f32 v97, v102, v103
	v_cvt_pk_bf16_f32 v98, v104, v105
	v_cvt_pk_bf16_f32 v99, v106, v107
	v_lshl_add_u64 v[100:101], v[100:101], 0, v[136:137]
	global_store_dwordx4 v[100:101], v[96:99], off nt
	s_nop 1
	v_fmamk_f32 v96, v176, 0x3a800000, v169
	v_cmp_gt_f32_e32 vcc, s58, v96
	v_mul_f32_e32 v97, 0x4b800000, v96
	s_nop 0
	v_cndmask_b32_e32 v96, v96, v97, vcc
	v_rsq_f32_e32 v96, v96
	s_nop 0
	v_mul_f32_e32 v97, 0x45800000, v96
	v_cndmask_b32_e32 v96, v96, v97, vcc
	v_pk_mul_f32 v[92:93], v[92:93], v[96:97] op_sel_hi:[1,0]
	s_nop 0
	v_mul_f32_e32 v97, 0xbfb8aa3b, v92
	v_exp_f32_e32 v97, v97
	s_nop 0
	v_add_f32_e32 v97, 1.0, v97
	v_rcp_f32_e32 v98, v97
	v_pk_mul_f32 v[84:85], v[84:85], v[96:97] op_sel_hi:[1,0]
	v_mul_f32_e32 v97, 0xbfb8aa3b, v93
	v_exp_f32_e32 v97, v97
	s_nop 0
	v_add_f32_e32 v97, 1.0, v97
	v_rcp_f32_e32 v99, v97
	v_pk_mul_f32 v[86:87], v[86:87], v[96:97] op_sel_hi:[1,0]
	v_pk_mul_f32 v[88:89], v[88:89], v[96:97] op_sel_hi:[1,0]
	v_pk_mul_f32 v[80:81], v[80:81], v[96:97] op_sel_hi:[1,0]
	v_pk_mul_f32 v[92:93], v[92:93], v[98:99]
	v_pk_mul_f32 v[82:83], v[82:83], v[96:97] op_sel_hi:[1,0]
	v_pk_mul_f32 v[84:85], v[84:85], v[92:93]
	v_pk_mul_f32 v[92:93], v[94:95], v[96:97] op_sel_hi:[1,0]
	s_nop 0
	v_pk_mul_f32 v[94:95], v[92:93], v[254:255] op_sel_hi:[1,0]
	s_nop 0
	v_exp_f32_e32 v94, v94
	v_exp_f32_e32 v95, v95
	s_nop 0
	v_pk_add_f32 v[94:95], v[94:95], 1.0 op_sel_hi:[1,0]
	s_nop 0
	v_rcp_f32_e32 v94, v94
	v_rcp_f32_e32 v95, v95
	s_nop 0
	v_pk_mul_f32 v[92:93], v[92:93], v[94:95]
	s_nop 0
	v_pk_mul_f32 v[86:87], v[86:87], v[92:93]
	v_pk_mul_f32 v[92:93], v[88:89], v[254:255] op_sel_hi:[1,0]
	s_nop 0
	v_exp_f32_e32 v92, v92
	v_exp_f32_e32 v93, v93
	s_nop 0
	v_pk_add_f32 v[92:93], v[92:93], 1.0 op_sel_hi:[1,0]
	s_nop 0
	v_rcp_f32_e32 v92, v92
	v_rcp_f32_e32 v93, v93
	s_nop 0
	v_pk_mul_f32 v[88:89], v[88:89], v[92:93]
	s_nop 0
	v_pk_mul_f32 v[88:89], v[80:81], v[88:89]
	v_pk_mul_f32 v[80:81], v[90:91], v[96:97] op_sel_hi:[1,0]
	s_nop 0
	v_pk_mul_f32 v[90:91], v[80:81], v[254:255] op_sel_hi:[1,0]
	s_nop 0
	v_exp_f32_e32 v90, v90
	v_exp_f32_e32 v91, v91
	s_nop 0
	v_pk_add_f32 v[90:91], v[90:91], 1.0 op_sel_hi:[1,0]
	s_nop 0
	v_rcp_f32_e32 v90, v90
	v_rcp_f32_e32 v91, v91
	s_nop 0
	v_pk_mul_f32 v[80:81], v[80:81], v[90:91]
	s_nop 0
	v_pk_mul_f32 v[90:91], v[82:83], v[80:81]
	v_cvt_pk_bf16_f32 v80, v84, v85
	v_lshl_add_u64 v[84:85], s[14:15], 0, v[144:145]
	v_cvt_pk_bf16_f32 v81, v86, v87
	v_cvt_pk_bf16_f32 v82, v88, v89
	v_cvt_pk_bf16_f32 v83, v90, v91
	v_lshl_add_u64 v[84:85], v[84:85], 0, v[136:137]
	global_store_dwordx4 v[84:85], v[80:83], off nt
	s_nop 1
	v_fmamk_f32 v80, v177, 0x3a800000, v169
	v_cmp_gt_f32_e32 vcc, s58, v80
	v_mul_f32_e32 v81, 0x4b800000, v80
	s_nop 0
	v_cndmask_b32_e32 v80, v80, v81, vcc
	v_rsq_f32_e32 v80, v80
	s_nop 0
	v_mul_f32_e32 v81, 0x45800000, v80
	v_cndmask_b32_e32 v80, v80, v81, vcc
	v_pk_mul_f32 v[76:77], v[76:77], v[80:81] op_sel_hi:[1,0]
	s_nop 0
	v_mul_f32_e32 v81, 0xbfb8aa3b, v76
	v_exp_f32_e32 v81, v81
	s_nop 0
	v_add_f32_e32 v81, 1.0, v81
	v_rcp_f32_e32 v82, v81
	v_pk_mul_f32 v[68:69], v[68:69], v[80:81] op_sel_hi:[1,0]
	v_mul_f32_e32 v81, 0xbfb8aa3b, v77
	v_exp_f32_e32 v81, v81
	s_nop 0
	v_add_f32_e32 v81, 1.0, v81
	v_rcp_f32_e32 v83, v81
	v_pk_mul_f32 v[70:71], v[70:71], v[80:81] op_sel_hi:[1,0]
	v_pk_mul_f32 v[72:73], v[72:73], v[80:81] op_sel_hi:[1,0]
	v_pk_mul_f32 v[64:65], v[64:65], v[80:81] op_sel_hi:[1,0]
	v_pk_mul_f32 v[76:77], v[76:77], v[82:83]
	v_pk_mul_f32 v[66:67], v[66:67], v[80:81] op_sel_hi:[1,0]
	v_pk_mul_f32 v[68:69], v[68:69], v[76:77]
	v_pk_mul_f32 v[76:77], v[78:79], v[80:81] op_sel_hi:[1,0]
	s_nop 0
	v_pk_mul_f32 v[78:79], v[76:77], v[254:255] op_sel_hi:[1,0]
	s_nop 0
	v_exp_f32_e32 v78, v78
	v_exp_f32_e32 v79, v79
	s_nop 0
	v_pk_add_f32 v[78:79], v[78:79], 1.0 op_sel_hi:[1,0]
	s_nop 0
	v_rcp_f32_e32 v78, v78
	v_rcp_f32_e32 v79, v79
	s_nop 0
	v_pk_mul_f32 v[76:77], v[76:77], v[78:79]
	s_nop 0
	v_pk_mul_f32 v[70:71], v[70:71], v[76:77]
	v_pk_mul_f32 v[76:77], v[72:73], v[254:255] op_sel_hi:[1,0]
	s_nop 0
	v_exp_f32_e32 v76, v76
	v_exp_f32_e32 v77, v77
	s_nop 0
	v_pk_add_f32 v[76:77], v[76:77], 1.0 op_sel_hi:[1,0]
	s_nop 0
	v_rcp_f32_e32 v76, v76
	v_rcp_f32_e32 v77, v77
	s_nop 0
	v_pk_mul_f32 v[72:73], v[72:73], v[76:77]
	s_nop 0
	v_pk_mul_f32 v[72:73], v[64:65], v[72:73]
	v_pk_mul_f32 v[64:65], v[74:75], v[80:81] op_sel_hi:[1,0]
	s_nop 0
	v_pk_mul_f32 v[74:75], v[64:65], v[254:255] op_sel_hi:[1,0]
	s_nop 0
	v_exp_f32_e32 v74, v74
	v_exp_f32_e32 v75, v75
	s_nop 0
	v_pk_add_f32 v[74:75], v[74:75], 1.0 op_sel_hi:[1,0]
	s_nop 0
	v_rcp_f32_e32 v74, v74
	v_rcp_f32_e32 v75, v75
	s_nop 0
	v_pk_mul_f32 v[64:65], v[64:65], v[74:75]
	s_nop 0
	v_pk_mul_f32 v[74:75], v[66:67], v[64:65]
	v_cvt_pk_bf16_f32 v64, v68, v69
	v_lshl_add_u64 v[68:69], s[14:15], 0, v[146:147]
	v_cvt_pk_bf16_f32 v65, v70, v71
	v_cvt_pk_bf16_f32 v66, v72, v73
	v_cvt_pk_bf16_f32 v67, v74, v75
	v_lshl_add_u64 v[68:69], v[68:69], 0, v[136:137]
	global_store_dwordx4 v[68:69], v[64:67], off nt
	s_nop 1
	v_fmamk_f32 v64, v178, 0x3a800000, v169
	v_cmp_gt_f32_e32 vcc, s58, v64
	v_mul_f32_e32 v65, 0x4b800000, v64
	s_nop 0
	v_cndmask_b32_e32 v64, v64, v65, vcc
	v_rsq_f32_e32 v64, v64
	s_nop 0
	v_mul_f32_e32 v65, 0x45800000, v64
	v_cndmask_b32_e32 v64, v64, v65, vcc
	v_pk_mul_f32 v[60:61], v[60:61], v[64:65] op_sel_hi:[1,0]
	s_nop 0
	v_mul_f32_e32 v65, 0xbfb8aa3b, v60
	v_exp_f32_e32 v65, v65
	s_nop 0
	v_add_f32_e32 v65, 1.0, v65
	v_rcp_f32_e32 v66, v65
	v_pk_mul_f32 v[52:53], v[52:53], v[64:65] op_sel_hi:[1,0]
	v_mul_f32_e32 v65, 0xbfb8aa3b, v61
	v_exp_f32_e32 v65, v65
	s_nop 0
	v_add_f32_e32 v65, 1.0, v65
	v_rcp_f32_e32 v67, v65
	v_pk_mul_f32 v[54:55], v[54:55], v[64:65] op_sel_hi:[1,0]
	v_pk_mul_f32 v[56:57], v[56:57], v[64:65] op_sel_hi:[1,0]
	v_pk_mul_f32 v[48:49], v[48:49], v[64:65] op_sel_hi:[1,0]
	v_pk_mul_f32 v[60:61], v[60:61], v[66:67]
	v_pk_mul_f32 v[50:51], v[50:51], v[64:65] op_sel_hi:[1,0]
	v_pk_mul_f32 v[52:53], v[52:53], v[60:61]
	v_pk_mul_f32 v[60:61], v[62:63], v[64:65] op_sel_hi:[1,0]
	s_nop 0
	v_pk_mul_f32 v[62:63], v[60:61], v[254:255] op_sel_hi:[1,0]
	s_nop 0
	v_exp_f32_e32 v62, v62
	v_exp_f32_e32 v63, v63
	s_nop 0
	v_pk_add_f32 v[62:63], v[62:63], 1.0 op_sel_hi:[1,0]
	s_nop 0
	v_rcp_f32_e32 v62, v62
	v_rcp_f32_e32 v63, v63
	s_nop 0
	v_pk_mul_f32 v[60:61], v[60:61], v[62:63]
	s_nop 0
	v_pk_mul_f32 v[54:55], v[54:55], v[60:61]
	v_pk_mul_f32 v[60:61], v[56:57], v[254:255] op_sel_hi:[1,0]
	s_nop 0
	v_exp_f32_e32 v60, v60
	v_exp_f32_e32 v61, v61
	s_nop 0
	v_pk_add_f32 v[60:61], v[60:61], 1.0 op_sel_hi:[1,0]
	s_nop 0
	v_rcp_f32_e32 v60, v60
	v_rcp_f32_e32 v61, v61
	s_nop 0
	v_pk_mul_f32 v[56:57], v[56:57], v[60:61]
	s_nop 0
	v_pk_mul_f32 v[56:57], v[48:49], v[56:57]
	v_pk_mul_f32 v[48:49], v[58:59], v[64:65] op_sel_hi:[1,0]
	s_nop 0
	v_pk_mul_f32 v[58:59], v[48:49], v[254:255] op_sel_hi:[1,0]
	s_nop 0
	v_exp_f32_e32 v58, v58
	v_exp_f32_e32 v59, v59
	s_nop 0
	v_pk_add_f32 v[58:59], v[58:59], 1.0 op_sel_hi:[1,0]
	s_nop 0
	v_rcp_f32_e32 v58, v58
	v_rcp_f32_e32 v59, v59
	s_nop 0
	v_pk_mul_f32 v[48:49], v[48:49], v[58:59]
	s_nop 0
	v_pk_mul_f32 v[58:59], v[50:51], v[48:49]
	v_cvt_pk_bf16_f32 v48, v52, v53
	v_lshl_add_u64 v[52:53], s[14:15], 0, v[148:149]
	v_cvt_pk_bf16_f32 v49, v54, v55
	v_cvt_pk_bf16_f32 v50, v56, v57
	v_cvt_pk_bf16_f32 v51, v58, v59
	v_lshl_add_u64 v[52:53], v[52:53], 0, v[136:137]
	global_store_dwordx4 v[52:53], v[48:51], off nt
	s_nop 1
	v_fmamk_f32 v48, v179, 0x3a800000, v169
	v_cmp_gt_f32_e32 vcc, s58, v48
	v_mul_f32_e32 v49, 0x4b800000, v48
	s_nop 0
	v_cndmask_b32_e32 v48, v48, v49, vcc
	v_rsq_f32_e32 v48, v48
	s_nop 0
	v_mul_f32_e32 v49, 0x45800000, v48
	v_cndmask_b32_e32 v48, v48, v49, vcc
	v_pk_mul_f32 v[44:45], v[44:45], v[48:49] op_sel_hi:[1,0]
	s_nop 0
	v_mul_f32_e32 v49, 0xbfb8aa3b, v44
	v_exp_f32_e32 v49, v49
	s_nop 0
	v_add_f32_e32 v49, 1.0, v49
	v_rcp_f32_e32 v50, v49
	v_pk_mul_f32 v[36:37], v[36:37], v[48:49] op_sel_hi:[1,0]
	v_mul_f32_e32 v49, 0xbfb8aa3b, v45
	v_exp_f32_e32 v49, v49
	s_nop 0
	v_add_f32_e32 v49, 1.0, v49
	v_rcp_f32_e32 v51, v49
	v_pk_mul_f32 v[38:39], v[38:39], v[48:49] op_sel_hi:[1,0]
	v_pk_mul_f32 v[40:41], v[40:41], v[48:49] op_sel_hi:[1,0]
	v_pk_mul_f32 v[32:33], v[32:33], v[48:49] op_sel_hi:[1,0]
	v_pk_mul_f32 v[44:45], v[44:45], v[50:51]
	v_pk_mul_f32 v[34:35], v[34:35], v[48:49] op_sel_hi:[1,0]
	v_pk_mul_f32 v[36:37], v[36:37], v[44:45]
	v_pk_mul_f32 v[44:45], v[46:47], v[48:49] op_sel_hi:[1,0]
	s_nop 0
	v_pk_mul_f32 v[46:47], v[44:45], v[254:255] op_sel_hi:[1,0]
	s_nop 0
	v_exp_f32_e32 v46, v46
	v_exp_f32_e32 v47, v47
	s_nop 0
	v_pk_add_f32 v[46:47], v[46:47], 1.0 op_sel_hi:[1,0]
	s_nop 0
	v_rcp_f32_e32 v46, v46
	v_rcp_f32_e32 v47, v47
	s_nop 0
	v_pk_mul_f32 v[44:45], v[44:45], v[46:47]
	s_nop 0
	v_pk_mul_f32 v[38:39], v[38:39], v[44:45]
	v_pk_mul_f32 v[44:45], v[40:41], v[254:255] op_sel_hi:[1,0]
	s_nop 0
	v_exp_f32_e32 v44, v44
	v_exp_f32_e32 v45, v45
	s_nop 0
	v_pk_add_f32 v[44:45], v[44:45], 1.0 op_sel_hi:[1,0]
	s_nop 0
	v_rcp_f32_e32 v44, v44
	v_rcp_f32_e32 v45, v45
	s_nop 0
	v_pk_mul_f32 v[40:41], v[40:41], v[44:45]
	s_nop 0
	v_pk_mul_f32 v[40:41], v[32:33], v[40:41]
	v_pk_mul_f32 v[32:33], v[42:43], v[48:49] op_sel_hi:[1,0]
	s_nop 0
	v_pk_mul_f32 v[42:43], v[32:33], v[254:255] op_sel_hi:[1,0]
	s_nop 0
	v_exp_f32_e32 v42, v42
	v_exp_f32_e32 v43, v43
	s_nop 0
	v_pk_add_f32 v[42:43], v[42:43], 1.0 op_sel_hi:[1,0]
	s_nop 0
	v_rcp_f32_e32 v42, v42
	v_rcp_f32_e32 v43, v43
	s_nop 0
	v_pk_mul_f32 v[32:33], v[32:33], v[42:43]
	s_nop 0
	v_pk_mul_f32 v[42:43], v[34:35], v[32:33]
	v_cvt_pk_bf16_f32 v32, v36, v37
	v_lshl_add_u64 v[36:37], s[14:15], 0, v[150:151]
	v_cvt_pk_bf16_f32 v33, v38, v39
	v_cvt_pk_bf16_f32 v34, v40, v41
	v_cvt_pk_bf16_f32 v35, v42, v43
	v_lshl_add_u64 v[36:37], v[36:37], 0, v[136:137]
	global_store_dwordx4 v[36:37], v[32:35], off nt
	s_nop 1
	v_fmamk_f32 v32, v180, 0x3a800000, v169
	v_cmp_gt_f32_e32 vcc, s58, v32
	v_mul_f32_e32 v33, 0x4b800000, v32
	s_nop 0
	v_cndmask_b32_e32 v32, v32, v33, vcc
	v_rsq_f32_e32 v32, v32
	s_nop 0
	v_mul_f32_e32 v33, 0x45800000, v32
	v_cndmask_b32_e32 v32, v32, v33, vcc
	v_pk_mul_f32 v[28:29], v[28:29], v[32:33] op_sel_hi:[1,0]
	s_nop 0
	v_mul_f32_e32 v33, 0xbfb8aa3b, v28
	v_exp_f32_e32 v33, v33
	s_nop 0
	v_add_f32_e32 v33, 1.0, v33
	v_rcp_f32_e32 v34, v33
	v_pk_mul_f32 v[20:21], v[20:21], v[32:33] op_sel_hi:[1,0]
	v_mul_f32_e32 v33, 0xbfb8aa3b, v29
	v_exp_f32_e32 v33, v33
	s_nop 0
	v_add_f32_e32 v33, 1.0, v33
	v_rcp_f32_e32 v35, v33
	v_pk_mul_f32 v[22:23], v[22:23], v[32:33] op_sel_hi:[1,0]
	v_pk_mul_f32 v[24:25], v[24:25], v[32:33] op_sel_hi:[1,0]
	v_pk_mul_f32 v[16:17], v[16:17], v[32:33] op_sel_hi:[1,0]
	v_pk_mul_f32 v[28:29], v[28:29], v[34:35]
	v_pk_mul_f32 v[18:19], v[18:19], v[32:33] op_sel_hi:[1,0]
	v_pk_mul_f32 v[20:21], v[20:21], v[28:29]
	v_pk_mul_f32 v[28:29], v[30:31], v[32:33] op_sel_hi:[1,0]
	s_nop 0
	v_pk_mul_f32 v[30:31], v[28:29], v[254:255] op_sel_hi:[1,0]
	s_nop 0
	v_exp_f32_e32 v30, v30
	v_exp_f32_e32 v31, v31
	s_nop 0
	v_pk_add_f32 v[30:31], v[30:31], 1.0 op_sel_hi:[1,0]
	s_nop 0
	v_rcp_f32_e32 v30, v30
	v_rcp_f32_e32 v31, v31
	s_nop 0
	v_pk_mul_f32 v[28:29], v[28:29], v[30:31]
	s_nop 0
	v_pk_mul_f32 v[22:23], v[22:23], v[28:29]
	v_pk_mul_f32 v[28:29], v[24:25], v[254:255] op_sel_hi:[1,0]
	s_nop 0
	v_exp_f32_e32 v28, v28
	v_exp_f32_e32 v29, v29
	s_nop 0
	v_pk_add_f32 v[28:29], v[28:29], 1.0 op_sel_hi:[1,0]
	s_nop 0
	v_rcp_f32_e32 v28, v28
	v_rcp_f32_e32 v29, v29
	s_nop 0
	v_pk_mul_f32 v[24:25], v[24:25], v[28:29]
	s_nop 0
	v_pk_mul_f32 v[24:25], v[16:17], v[24:25]
	v_pk_mul_f32 v[16:17], v[26:27], v[32:33] op_sel_hi:[1,0]
	s_nop 0
	v_pk_mul_f32 v[26:27], v[16:17], v[254:255] op_sel_hi:[1,0]
	s_nop 0
	v_exp_f32_e32 v26, v26
	v_exp_f32_e32 v27, v27
	s_nop 0
	v_pk_add_f32 v[26:27], v[26:27], 1.0 op_sel_hi:[1,0]
	s_nop 0
	v_rcp_f32_e32 v26, v26
	v_rcp_f32_e32 v27, v27
	s_nop 0
	v_pk_mul_f32 v[16:17], v[16:17], v[26:27]
	s_nop 0
	v_pk_mul_f32 v[26:27], v[18:19], v[16:17]
	v_cvt_pk_bf16_f32 v16, v20, v21
	v_lshl_add_u64 v[20:21], s[14:15], 0, v[152:153]
	v_cvt_pk_bf16_f32 v17, v22, v23
	v_cvt_pk_bf16_f32 v18, v24, v25
	v_cvt_pk_bf16_f32 v19, v26, v27
	v_lshl_add_u64 v[20:21], v[20:21], 0, v[136:137]
	global_store_dwordx4 v[20:21], v[16:19], off nt
	s_nop 1
	v_fmamk_f32 v16, v181, 0x3a800000, v169
	v_cmp_gt_f32_e32 vcc, s58, v16
	v_mul_f32_e32 v17, 0x4b800000, v16
	s_nop 0
	v_cndmask_b32_e32 v16, v16, v17, vcc
	v_rsq_f32_e32 v16, v16
	s_nop 0
	v_mul_f32_e32 v17, 0x45800000, v16
	v_cndmask_b32_e32 v16, v16, v17, vcc
	v_pk_mul_f32 v[12:13], v[12:13], v[16:17] op_sel_hi:[1,0]
	s_andn2_b64 vcc, exec, s[2:3]
	v_mul_f32_e32 v17, 0xbfb8aa3b, v12
	v_exp_f32_e32 v17, v17
	s_nop 0
	v_add_f32_e32 v17, 1.0, v17
	v_rcp_f32_e32 v18, v17
	v_pk_mul_f32 v[4:5], v[4:5], v[16:17] op_sel_hi:[1,0]
	v_mul_f32_e32 v17, 0xbfb8aa3b, v13
	v_exp_f32_e32 v17, v17
	s_nop 0
	v_add_f32_e32 v17, 1.0, v17
	v_rcp_f32_e32 v19, v17
	v_pk_mul_f32 v[6:7], v[6:7], v[16:17] op_sel_hi:[1,0]
	v_pk_mul_f32 v[8:9], v[8:9], v[16:17] op_sel_hi:[1,0]
	v_pk_mul_f32 v[0:1], v[0:1], v[16:17] op_sel_hi:[1,0]
	v_pk_mul_f32 v[12:13], v[12:13], v[18:19]
	v_pk_mul_f32 v[2:3], v[2:3], v[16:17] op_sel_hi:[1,0]
	v_pk_mul_f32 v[4:5], v[4:5], v[12:13]
	v_pk_mul_f32 v[12:13], v[14:15], v[16:17] op_sel_hi:[1,0]
	s_nop 0
	v_pk_mul_f32 v[14:15], v[12:13], v[254:255] op_sel_hi:[1,0]
	s_nop 0
	v_exp_f32_e32 v14, v14
	v_exp_f32_e32 v15, v15
	s_nop 0
	v_pk_add_f32 v[14:15], v[14:15], 1.0 op_sel_hi:[1,0]
	s_nop 0
	v_rcp_f32_e32 v14, v14
	v_rcp_f32_e32 v15, v15
	s_nop 0
	v_pk_mul_f32 v[12:13], v[12:13], v[14:15]
	s_nop 0
	v_pk_mul_f32 v[6:7], v[6:7], v[12:13]
	v_pk_mul_f32 v[12:13], v[8:9], v[254:255] op_sel_hi:[1,0]
	s_nop 0
	v_exp_f32_e32 v12, v12
	v_exp_f32_e32 v13, v13
	s_nop 0
	v_pk_add_f32 v[12:13], v[12:13], 1.0 op_sel_hi:[1,0]
	s_nop 0
	v_rcp_f32_e32 v12, v12
	v_rcp_f32_e32 v13, v13
	s_nop 0
	v_pk_mul_f32 v[8:9], v[8:9], v[12:13]
	s_nop 0
	v_pk_mul_f32 v[8:9], v[0:1], v[8:9]
	v_pk_mul_f32 v[0:1], v[10:11], v[16:17] op_sel_hi:[1,0]
	s_nop 0
	v_pk_mul_f32 v[10:11], v[0:1], v[254:255] op_sel_hi:[1,0]
	s_nop 0
	v_exp_f32_e32 v10, v10
	v_exp_f32_e32 v11, v11
	s_nop 0
	v_pk_add_f32 v[10:11], v[10:11], 1.0 op_sel_hi:[1,0]
	s_nop 0
	v_rcp_f32_e32 v10, v10
	v_rcp_f32_e32 v11, v11
	s_nop 0
	v_pk_mul_f32 v[0:1], v[0:1], v[10:11]
	s_nop 0
	v_pk_mul_f32 v[10:11], v[2:3], v[0:1]
	v_cvt_pk_bf16_f32 v0, v4, v5
	v_lshl_add_u64 v[4:5], s[14:15], 0, v[154:155]
	v_cvt_pk_bf16_f32 v1, v6, v7
	v_cvt_pk_bf16_f32 v2, v8, v9
	v_cvt_pk_bf16_f32 v3, v10, v11
	v_lshl_add_u64 v[4:5], v[4:5], 0, v[136:137]
	s_mov_b64 s[14:15], -1
	global_store_dwordx4 v[4:5], v[0:3], off nt
	s_cbranch_vccnz .LBB0_169
	s_andn2_b64 vcc, exec, s[0:1]
	s_cbranch_vccnz .LBB0_168
	s_barrier
	s_branch .LBB0_168

.LBB0_1630:
	v_mov_b32_e32 v254, 0xbfb8aa3b
	v_lshl_add_u32 v164, s4, 8, v138
	v_ashrrev_i32_e32 v165, 31, v164
	v_lshl_add_u64 v[166:167], v[164:165], 2, s[6:7]
	global_load_dword v165, v[166:167], off
	global_load_dword v189, v[166:167], off offset:64
	global_load_dword v190, v[166:167], off offset:128
	global_load_dword v191, v[166:167], off offset:192
	global_load_dword v192, v[166:167], off offset:512
	global_load_dword v193, v[166:167], off offset:576
	global_load_dword v194, v[166:167], off offset:640
	global_load_dword v195, v[166:167], off offset:704
	s_lshl_b32 s5, s5, 1
	s_mul_i32 s4, s4, 44
	s_add_i32 s4, s4, s5
	s_or_b32 s4, s4, s35
	s_ashr_i32 s5, s4, 31
	s_lshl_b64 s[4:5], s[4:5], 15
	s_add_u32 s18, s80, s4
	s_addc_u32 s19, s81, s5
	s_waitcnt vmcnt(0)
	v_fmamk_f32 v165, v165, 0x3a800000, v171
	v_mul_f32_e32 v172, 0x4b800000, v165
	v_cmp_gt_f32_e32 vcc, s40, v165
	s_nop 1
	v_cndmask_b32_e32 v165, v165, v172, vcc
	v_rsq_f32_e32 v165, v165
	v_lshl_add_u64 v[172:173], s[18:19], 0, v[140:141]
	v_lshl_add_u64 v[172:173], v[172:173], 0, v[136:137]
	v_mul_f32_e32 v174, 0x45800000, v165
	v_cndmask_b32_e32 v174, v165, v174, vcc
	v_pk_mul_f32 v[124:125], v[124:125], v[174:175] op_sel_hi:[1,0]
	v_pk_mul_f32 v[126:127], v[126:127], v[174:175] op_sel_hi:[1,0]
	v_pk_mul_f32 v[120:121], v[120:121], v[174:175] op_sel_hi:[1,0]
	v_pk_mul_f32 v[122:123], v[122:123], v[174:175] op_sel_hi:[1,0]
	v_pk_mul_f32 v[116:117], v[116:117], v[174:175] op_sel_hi:[1,0]
	v_pk_mul_f32 v[118:119], v[118:119], v[174:175] op_sel_hi:[1,0]
	v_pk_mul_f32 v[112:113], v[112:113], v[174:175] op_sel_hi:[1,0]
	v_pk_mul_f32 v[114:115], v[114:115], v[174:175] op_sel_hi:[1,0]
	v_pk_mul_f32 v[246:247], v[124:125], v[254:255] op_sel_hi:[1,0]
	v_pk_mul_f32 v[248:249], v[126:127], v[254:255] op_sel_hi:[1,0]
	v_pk_mul_f32 v[250:251], v[120:121], v[254:255] op_sel_hi:[1,0]
	v_pk_mul_f32 v[252:253], v[122:123], v[254:255] op_sel_hi:[1,0]
	v_exp_f32_e32 v246, v246
	v_exp_f32_e32 v247, v247
	v_exp_f32_e32 v248, v248
	v_exp_f32_e32 v249, v249
	v_exp_f32_e32 v250, v250
	v_exp_f32_e32 v251, v251
	v_exp_f32_e32 v252, v252
	v_exp_f32_e32 v253, v253
	v_pk_add_f32 v[246:247], v[246:247], 1.0 op_sel_hi:[1,0]
	v_pk_add_f32 v[248:249], v[248:249], 1.0 op_sel_hi:[1,0]
	v_pk_add_f32 v[250:251], v[250:251], 1.0 op_sel_hi:[1,0]
	v_pk_add_f32 v[252:253], v[252:253], 1.0 op_sel_hi:[1,0]
	v_rcp_f32_e32 v174, v246
	v_rcp_f32_e32 v175, v247
	v_rcp_f32_e32 v176, v248
	v_rcp_f32_e32 v177, v249
	v_rcp_f32_e32 v178, v250
	v_rcp_f32_e32 v179, v251
	v_rcp_f32_e32 v180, v252
	v_rcp_f32_e32 v181, v253
	v_pk_mul_f32 v[124:125], v[124:125], v[174:175]
	v_pk_mul_f32 v[126:127], v[126:127], v[176:177]
	v_pk_mul_f32 v[120:121], v[120:121], v[178:179]
	v_pk_mul_f32 v[122:123], v[122:123], v[180:181]
	v_pk_mul_f32 v[116:117], v[116:117], v[124:125]
	v_pk_mul_f32 v[118:119], v[118:119], v[126:127]
	v_pk_mul_f32 v[120:121], v[112:113], v[120:121]
	v_pk_mul_f32 v[122:123], v[114:115], v[122:123]
	v_cvt_pk_bf16_f32 v112, v116, v117
	v_cvt_pk_bf16_f32 v113, v118, v119
	v_cvt_pk_bf16_f32 v114, v120, v121
	v_cvt_pk_bf16_f32 v115, v122, v123
	global_store_dwordx4 v[172:173], v[112:115], off nt
	s_nop 1
	v_fmamk_f32 v112, v189, 0x3a800000, v171
	v_mul_f32_e32 v113, 0x4b800000, v112
	v_cmp_gt_f32_e32 vcc, s40, v112
	s_nop 1
	v_cndmask_b32_e32 v112, v112, v113, vcc
	v_rsq_f32_e32 v114, v112
	v_lshl_add_u64 v[112:113], s[18:19], 0, v[142:143]
	v_lshl_add_u64 v[112:113], v[112:113], 0, v[136:137]
	v_mul_f32_e32 v115, 0x45800000, v114
	v_cndmask_b32_e32 v114, v114, v115, vcc
	v_pk_mul_f32 v[108:109], v[108:109], v[114:115] op_sel_hi:[1,0]
	v_pk_mul_f32 v[110:111], v[110:111], v[114:115] op_sel_hi:[1,0]
	v_pk_mul_f32 v[104:105], v[104:105], v[114:115] op_sel_hi:[1,0]
	v_pk_mul_f32 v[106:107], v[106:107], v[114:115] op_sel_hi:[1,0]
	v_pk_mul_f32 v[100:101], v[100:101], v[114:115] op_sel_hi:[1,0]
	v_pk_mul_f32 v[102:103], v[102:103], v[114:115] op_sel_hi:[1,0]
	v_pk_mul_f32 v[96:97], v[96:97], v[114:115] op_sel_hi:[1,0]
	v_pk_mul_f32 v[98:99], v[98:99], v[114:115] op_sel_hi:[1,0]
	v_pk_mul_f32 v[246:247], v[108:109], v[254:255] op_sel_hi:[1,0]
	v_pk_mul_f32 v[248:249], v[110:111], v[254:255] op_sel_hi:[1,0]
	v_pk_mul_f32 v[250:251], v[104:105], v[254:255] op_sel_hi:[1,0]
	v_pk_mul_f32 v[252:253], v[106:107], v[254:255] op_sel_hi:[1,0]
	v_exp_f32_e32 v246, v246
	v_exp_f32_e32 v247, v247
	v_exp_f32_e32 v248, v248
	v_exp_f32_e32 v249, v249
	v_exp_f32_e32 v250, v250
	v_exp_f32_e32 v251, v251
	v_exp_f32_e32 v252, v252
	v_exp_f32_e32 v253, v253
	v_pk_add_f32 v[246:247], v[246:247], 1.0 op_sel_hi:[1,0]
	v_pk_add_f32 v[248:249], v[248:249], 1.0 op_sel_hi:[1,0]
	v_pk_add_f32 v[250:251], v[250:251], 1.0 op_sel_hi:[1,0]
	v_pk_add_f32 v[252:253], v[252:253], 1.0 op_sel_hi:[1,0]
	v_rcp_f32_e32 v114, v246
	v_rcp_f32_e32 v115, v247
	v_rcp_f32_e32 v116, v248
	v_rcp_f32_e32 v117, v249
	v_rcp_f32_e32 v118, v250
	v_rcp_f32_e32 v119, v251
	v_rcp_f32_e32 v120, v252
	v_rcp_f32_e32 v121, v253
	v_pk_mul_f32 v[108:109], v[108:109], v[114:115]
	v_pk_mul_f32 v[110:111], v[110:111], v[116:117]
	v_pk_mul_f32 v[104:105], v[104:105], v[118:119]
	v_pk_mul_f32 v[106:107], v[106:107], v[120:121]
	v_pk_mul_f32 v[100:101], v[100:101], v[108:109]
	v_pk_mul_f32 v[102:103], v[102:103], v[110:111]
	v_pk_mul_f32 v[104:105], v[96:97], v[104:105]
	v_pk_mul_f32 v[106:107], v[98:99], v[106:107]
	v_cvt_pk_bf16_f32 v96, v100, v101
	v_cvt_pk_bf16_f32 v97, v102, v103
	v_cvt_pk_bf16_f32 v98, v104, v105
	v_cvt_pk_bf16_f32 v99, v106, v107
	global_store_dwordx4 v[112:113], v[96:99], off nt
	s_nop 1
	v_fmamk_f32 v96, v190, 0x3a800000, v171
	v_mul_f32_e32 v97, 0x4b800000, v96
	v_cmp_gt_f32_e32 vcc, s40, v96
	s_nop 1
	v_cndmask_b32_e32 v96, v96, v97, vcc
	v_rsq_f32_e32 v98, v96
	v_lshl_add_u64 v[96:97], s[18:19], 0, v[144:145]
	v_lshl_add_u64 v[96:97], v[96:97], 0, v[136:137]
	v_mul_f32_e32 v99, 0x45800000, v98
	v_cndmask_b32_e32 v98, v98, v99, vcc
	v_pk_mul_f32 v[92:93], v[92:93], v[98:99] op_sel_hi:[1,0]
	v_pk_mul_f32 v[94:95], v[94:95], v[98:99] op_sel_hi:[1,0]
	v_pk_mul_f32 v[88:89], v[88:89], v[98:99] op_sel_hi:[1,0]
	v_pk_mul_f32 v[90:91], v[90:91], v[98:99] op_sel_hi:[1,0]
	v_pk_mul_f32 v[84:85], v[84:85], v[98:99] op_sel_hi:[1,0]
	v_pk_mul_f32 v[86:87], v[86:87], v[98:99] op_sel_hi:[1,0]
	v_pk_mul_f32 v[80:81], v[80:81], v[98:99] op_sel_hi:[1,0]
	v_pk_mul_f32 v[82:83], v[82:83], v[98:99] op_sel_hi:[1,0]
	v_pk_mul_f32 v[246:247], v[92:93], v[254:255] op_sel_hi:[1,0]
	v_pk_mul_f32 v[248:249], v[94:95], v[254:255] op_sel_hi:[1,0]
	v_pk_mul_f32 v[250:251], v[88:89], v[254:255] op_sel_hi:[1,0]
	v_pk_mul_f32 v[252:253], v[90:91], v[254:255] op_sel_hi:[1,0]
	v_exp_f32_e32 v246, v246
	v_exp_f32_e32 v247, v247
	v_exp_f32_e32 v248, v248
	v_exp_f32_e32 v249, v249
	v_exp_f32_e32 v250, v250
	v_exp_f32_e32 v251, v251
	v_exp_f32_e32 v252, v252
	v_exp_f32_e32 v253, v253
	v_pk_add_f32 v[246:247], v[246:247], 1.0 op_sel_hi:[1,0]
	v_pk_add_f32 v[248:249], v[248:249], 1.0 op_sel_hi:[1,0]
	v_pk_add_f32 v[250:251], v[250:251], 1.0 op_sel_hi:[1,0]
	v_pk_add_f32 v[252:253], v[252:253], 1.0 op_sel_hi:[1,0]
	v_rcp_f32_e32 v98, v246
	v_rcp_f32_e32 v99, v247
	v_rcp_f32_e32 v100, v248
	v_rcp_f32_e32 v101, v249
	v_rcp_f32_e32 v102, v250
	v_rcp_f32_e32 v103, v251
	v_rcp_f32_e32 v104, v252
	v_rcp_f32_e32 v105, v253
	v_pk_mul_f32 v[92:93], v[92:93], v[98:99]
	v_pk_mul_f32 v[94:95], v[94:95], v[100:101]
	v_pk_mul_f32 v[88:89], v[88:89], v[102:103]
	v_pk_mul_f32 v[90:91], v[90:91], v[104:105]
	v_pk_mul_f32 v[84:85], v[84:85], v[92:93]
	v_pk_mul_f32 v[86:87], v[86:87], v[94:95]
	v_pk_mul_f32 v[88:89], v[80:81], v[88:89]
	v_pk_mul_f32 v[90:91], v[82:83], v[90:91]
	v_cvt_pk_bf16_f32 v80, v84, v85
	v_cvt_pk_bf16_f32 v81, v86, v87
	v_cvt_pk_bf16_f32 v82, v88, v89
	v_cvt_pk_bf16_f32 v83, v90, v91
	global_store_dwordx4 v[96:97], v[80:83], off nt
	s_nop 1
	s_nop 0
	v_add_u32_e32 v80, 0x80, v164
	v_ashrrev_i32_e32 v81, 31, v80
	v_lshl_add_u64 v[80:81], v[80:81], 2, s[6:7]
	v_fmamk_f32 v82, v191, 0x3a800000, v171
	v_mul_f32_e32 v83, 0x4b800000, v82
	v_cmp_gt_f32_e32 vcc, s40, v82
	s_nop 1
	v_cndmask_b32_e32 v82, v82, v83, vcc
	v_rsq_f32_e32 v84, v82
	v_lshl_add_u64 v[82:83], s[18:19], 0, v[146:147]
	v_lshl_add_u64 v[82:83], v[82:83], 0, v[136:137]
	v_mul_f32_e32 v85, 0x45800000, v84
	v_cndmask_b32_e32 v84, v84, v85, vcc
	v_pk_mul_f32 v[76:77], v[76:77], v[84:85] op_sel_hi:[1,0]
	v_pk_mul_f32 v[78:79], v[78:79], v[84:85] op_sel_hi:[1,0]
	v_pk_mul_f32 v[72:73], v[72:73], v[84:85] op_sel_hi:[1,0]
	v_pk_mul_f32 v[74:75], v[74:75], v[84:85] op_sel_hi:[1,0]
	v_pk_mul_f32 v[68:69], v[68:69], v[84:85] op_sel_hi:[1,0]
	v_pk_mul_f32 v[70:71], v[70:71], v[84:85] op_sel_hi:[1,0]
	v_pk_mul_f32 v[64:65], v[64:65], v[84:85] op_sel_hi:[1,0]
	v_pk_mul_f32 v[66:67], v[66:67], v[84:85] op_sel_hi:[1,0]
	v_pk_mul_f32 v[246:247], v[76:77], v[254:255] op_sel_hi:[1,0]
	v_pk_mul_f32 v[248:249], v[78:79], v[254:255] op_sel_hi:[1,0]
	v_pk_mul_f32 v[250:251], v[72:73], v[254:255] op_sel_hi:[1,0]
	v_pk_mul_f32 v[252:253], v[74:75], v[254:255] op_sel_hi:[1,0]
	v_exp_f32_e32 v246, v246
	v_exp_f32_e32 v247, v247
	v_exp_f32_e32 v248, v248
	v_exp_f32_e32 v249, v249
	v_exp_f32_e32 v250, v250
	v_exp_f32_e32 v251, v251
	v_exp_f32_e32 v252, v252
	v_exp_f32_e32 v253, v253
	v_pk_add_f32 v[246:247], v[246:247], 1.0 op_sel_hi:[1,0]
	v_pk_add_f32 v[248:249], v[248:249], 1.0 op_sel_hi:[1,0]
	v_pk_add_f32 v[250:251], v[250:251], 1.0 op_sel_hi:[1,0]
	v_pk_add_f32 v[252:253], v[252:253], 1.0 op_sel_hi:[1,0]
	v_rcp_f32_e32 v84, v246
	v_rcp_f32_e32 v85, v247
	v_rcp_f32_e32 v86, v248
	v_rcp_f32_e32 v87, v249
	v_rcp_f32_e32 v88, v250
	v_rcp_f32_e32 v89, v251
	v_rcp_f32_e32 v90, v252
	v_rcp_f32_e32 v91, v253
	v_pk_mul_f32 v[76:77], v[76:77], v[84:85]
	v_pk_mul_f32 v[78:79], v[78:79], v[86:87]
	v_pk_mul_f32 v[72:73], v[72:73], v[88:89]
	v_pk_mul_f32 v[74:75], v[74:75], v[90:91]
	v_pk_mul_f32 v[68:69], v[68:69], v[76:77]
	v_pk_mul_f32 v[70:71], v[70:71], v[78:79]
	v_pk_mul_f32 v[72:73], v[64:65], v[72:73]
	v_pk_mul_f32 v[74:75], v[66:67], v[74:75]
	v_cvt_pk_bf16_f32 v64, v68, v69
	v_cvt_pk_bf16_f32 v65, v70, v71
	v_cvt_pk_bf16_f32 v66, v72, v73
	v_cvt_pk_bf16_f32 v67, v74, v75
	global_store_dwordx4 v[82:83], v[64:67], off nt
	s_nop 1
	s_nop 0
	v_add_u32_e32 v64, 0x90, v164
	v_ashrrev_i32_e32 v65, 31, v64
	v_lshl_add_u64 v[64:65], v[64:65], 2, s[6:7]
	v_fmamk_f32 v66, v192, 0x3a800000, v171
	v_mul_f32_e32 v67, 0x4b800000, v66
	v_cmp_gt_f32_e32 vcc, s40, v66
	s_nop 1
	v_cndmask_b32_e32 v66, v66, v67, vcc
	v_rsq_f32_e32 v68, v66
	v_lshl_add_u64 v[66:67], s[18:19], 0, v[148:149]
	v_lshl_add_u64 v[66:67], v[66:67], 0, v[136:137]
	v_mul_f32_e32 v69, 0x45800000, v68
	v_cndmask_b32_e32 v68, v68, v69, vcc
	v_pk_mul_f32 v[60:61], v[60:61], v[68:69] op_sel_hi:[1,0]
	v_pk_mul_f32 v[62:63], v[62:63], v[68:69] op_sel_hi:[1,0]
	v_pk_mul_f32 v[56:57], v[56:57], v[68:69] op_sel_hi:[1,0]
	v_pk_mul_f32 v[58:59], v[58:59], v[68:69] op_sel_hi:[1,0]
	v_pk_mul_f32 v[52:53], v[52:53], v[68:69] op_sel_hi:[1,0]
	v_pk_mul_f32 v[54:55], v[54:55], v[68:69] op_sel_hi:[1,0]
	v_pk_mul_f32 v[48:49], v[48:49], v[68:69] op_sel_hi:[1,0]
	v_pk_mul_f32 v[50:51], v[50:51], v[68:69] op_sel_hi:[1,0]
	v_pk_mul_f32 v[246:247], v[60:61], v[254:255] op_sel_hi:[1,0]
	v_pk_mul_f32 v[248:249], v[62:63], v[254:255] op_sel_hi:[1,0]
	v_pk_mul_f32 v[250:251], v[56:57], v[254:255] op_sel_hi:[1,0]
	v_pk_mul_f32 v[252:253], v[58:59], v[254:255] op_sel_hi:[1,0]
	v_exp_f32_e32 v246, v246
	v_exp_f32_e32 v247, v247
	v_exp_f32_e32 v248, v248
	v_exp_f32_e32 v249, v249
	v_exp_f32_e32 v250, v250
	v_exp_f32_e32 v251, v251
	v_exp_f32_e32 v252, v252
	v_exp_f32_e32 v253, v253
	v_pk_add_f32 v[246:247], v[246:247], 1.0 op_sel_hi:[1,0]
	v_pk_add_f32 v[248:249], v[248:249], 1.0 op_sel_hi:[1,0]
	v_pk_add_f32 v[250:251], v[250:251], 1.0 op_sel_hi:[1,0]
	v_pk_add_f32 v[252:253], v[252:253], 1.0 op_sel_hi:[1,0]
	v_rcp_f32_e32 v68, v246
	v_rcp_f32_e32 v69, v247
	v_rcp_f32_e32 v70, v248
	v_rcp_f32_e32 v71, v249
	v_rcp_f32_e32 v72, v250
	v_rcp_f32_e32 v73, v251
	v_rcp_f32_e32 v74, v252
	v_rcp_f32_e32 v75, v253
	v_pk_mul_f32 v[60:61], v[60:61], v[68:69]
	v_pk_mul_f32 v[62:63], v[62:63], v[70:71]
	v_pk_mul_f32 v[56:57], v[56:57], v[72:73]
	v_pk_mul_f32 v[58:59], v[58:59], v[74:75]
	v_pk_mul_f32 v[52:53], v[52:53], v[60:61]
	v_pk_mul_f32 v[54:55], v[54:55], v[62:63]
	v_pk_mul_f32 v[56:57], v[48:49], v[56:57]
	v_pk_mul_f32 v[58:59], v[50:51], v[58:59]
	v_cvt_pk_bf16_f32 v48, v52, v53
	v_cvt_pk_bf16_f32 v49, v54, v55
	v_cvt_pk_bf16_f32 v50, v56, v57
	v_cvt_pk_bf16_f32 v51, v58, v59
	global_store_dwordx4 v[66:67], v[48:51], off nt
	s_nop 1
	s_nop 0
	v_add_u32_e32 v48, 0xa0, v164
	v_ashrrev_i32_e32 v49, 31, v48
	v_lshl_add_u64 v[48:49], v[48:49], 2, s[6:7]
	v_fmamk_f32 v50, v193, 0x3a800000, v171
	v_mul_f32_e32 v51, 0x4b800000, v50
	v_cmp_gt_f32_e32 vcc, s40, v50
	s_nop 1
	v_cndmask_b32_e32 v50, v50, v51, vcc
	v_rsq_f32_e32 v52, v50
	v_lshl_add_u64 v[50:51], s[18:19], 0, v[150:151]
	v_lshl_add_u64 v[50:51], v[50:51], 0, v[136:137]
	v_mul_f32_e32 v53, 0x45800000, v52
	v_cndmask_b32_e32 v52, v52, v53, vcc
	v_pk_mul_f32 v[44:45], v[44:45], v[52:53] op_sel_hi:[1,0]
	v_pk_mul_f32 v[46:47], v[46:47], v[52:53] op_sel_hi:[1,0]
	v_pk_mul_f32 v[40:41], v[40:41], v[52:53] op_sel_hi:[1,0]
	v_pk_mul_f32 v[42:43], v[42:43], v[52:53] op_sel_hi:[1,0]
	v_pk_mul_f32 v[36:37], v[36:37], v[52:53] op_sel_hi:[1,0]
	v_pk_mul_f32 v[38:39], v[38:39], v[52:53] op_sel_hi:[1,0]
	v_pk_mul_f32 v[32:33], v[32:33], v[52:53] op_sel_hi:[1,0]
	v_pk_mul_f32 v[34:35], v[34:35], v[52:53] op_sel_hi:[1,0]
	v_pk_mul_f32 v[246:247], v[44:45], v[254:255] op_sel_hi:[1,0]
	v_pk_mul_f32 v[248:249], v[46:47], v[254:255] op_sel_hi:[1,0]
	v_pk_mul_f32 v[250:251], v[40:41], v[254:255] op_sel_hi:[1,0]
	v_pk_mul_f32 v[252:253], v[42:43], v[254:255] op_sel_hi:[1,0]
	v_exp_f32_e32 v246, v246
	v_exp_f32_e32 v247, v247
	v_exp_f32_e32 v248, v248
	v_exp_f32_e32 v249, v249
	v_exp_f32_e32 v250, v250
	v_exp_f32_e32 v251, v251
	v_exp_f32_e32 v252, v252
	v_exp_f32_e32 v253, v253
	v_pk_add_f32 v[246:247], v[246:247], 1.0 op_sel_hi:[1,0]
	v_pk_add_f32 v[248:249], v[248:249], 1.0 op_sel_hi:[1,0]
	v_pk_add_f32 v[250:251], v[250:251], 1.0 op_sel_hi:[1,0]
	v_pk_add_f32 v[252:253], v[252:253], 1.0 op_sel_hi:[1,0]
	v_rcp_f32_e32 v52, v246
	v_rcp_f32_e32 v53, v247
	v_rcp_f32_e32 v54, v248
	v_rcp_f32_e32 v55, v249
	v_rcp_f32_e32 v56, v250
	v_rcp_f32_e32 v57, v251
	v_rcp_f32_e32 v58, v252
	v_rcp_f32_e32 v59, v253
	v_pk_mul_f32 v[44:45], v[44:45], v[52:53]
	v_pk_mul_f32 v[46:47], v[46:47], v[54:55]
	v_pk_mul_f32 v[40:41], v[40:41], v[56:57]
	v_pk_mul_f32 v[42:43], v[42:43], v[58:59]
	v_pk_mul_f32 v[36:37], v[36:37], v[44:45]
	v_pk_mul_f32 v[38:39], v[38:39], v[46:47]
	v_pk_mul_f32 v[40:41], v[32:33], v[40:41]
	v_pk_mul_f32 v[42:43], v[34:35], v[42:43]
	v_cvt_pk_bf16_f32 v32, v36, v37
	v_cvt_pk_bf16_f32 v33, v38, v39
	v_cvt_pk_bf16_f32 v34, v40, v41
	v_cvt_pk_bf16_f32 v35, v42, v43
	global_store_dwordx4 v[50:51], v[32:35], off nt
	s_nop 1
	s_nop 0
	v_add_u32_e32 v32, 0xb0, v164
	v_ashrrev_i32_e32 v33, 31, v32
	v_lshl_add_u64 v[32:33], v[32:33], 2, s[6:7]
	v_fmamk_f32 v34, v194, 0x3a800000, v171
	v_mul_f32_e32 v35, 0x4b800000, v34
	v_cmp_gt_f32_e32 vcc, s40, v34
	s_nop 1
	v_cndmask_b32_e32 v34, v34, v35, vcc
	v_rsq_f32_e32 v36, v34
	v_lshl_add_u64 v[34:35], s[18:19], 0, v[152:153]
	v_lshl_add_u64 v[34:35], v[34:35], 0, v[136:137]
	v_mul_f32_e32 v37, 0x45800000, v36
	v_cndmask_b32_e32 v36, v36, v37, vcc
	v_pk_mul_f32 v[28:29], v[28:29], v[36:37] op_sel_hi:[1,0]
	v_pk_mul_f32 v[30:31], v[30:31], v[36:37] op_sel_hi:[1,0]
	v_pk_mul_f32 v[24:25], v[24:25], v[36:37] op_sel_hi:[1,0]
	v_pk_mul_f32 v[26:27], v[26:27], v[36:37] op_sel_hi:[1,0]
	v_pk_mul_f32 v[20:21], v[20:21], v[36:37] op_sel_hi:[1,0]
	v_pk_mul_f32 v[22:23], v[22:23], v[36:37] op_sel_hi:[1,0]
	v_pk_mul_f32 v[16:17], v[16:17], v[36:37] op_sel_hi:[1,0]
	v_pk_mul_f32 v[18:19], v[18:19], v[36:37] op_sel_hi:[1,0]
	v_pk_mul_f32 v[246:247], v[28:29], v[254:255] op_sel_hi:[1,0]
	v_pk_mul_f32 v[248:249], v[30:31], v[254:255] op_sel_hi:[1,0]
	v_pk_mul_f32 v[250:251], v[24:25], v[254:255] op_sel_hi:[1,0]
	v_pk_mul_f32 v[252:253], v[26:27], v[254:255] op_sel_hi:[1,0]
	v_exp_f32_e32 v246, v246
	v_exp_f32_e32 v247, v247
	v_exp_f32_e32 v248, v248
	v_exp_f32_e32 v249, v249
	v_exp_f32_e32 v250, v250
	v_exp_f32_e32 v251, v251
	v_exp_f32_e32 v252, v252
	v_exp_f32_e32 v253, v253
	v_pk_add_f32 v[246:247], v[246:247], 1.0 op_sel_hi:[1,0]
	v_pk_add_f32 v[248:249], v[248:249], 1.0 op_sel_hi:[1,0]
	v_pk_add_f32 v[250:251], v[250:251], 1.0 op_sel_hi:[1,0]
	v_pk_add_f32 v[252:253], v[252:253], 1.0 op_sel_hi:[1,0]
	v_rcp_f32_e32 v36, v246
	v_rcp_f32_e32 v37, v247
	v_rcp_f32_e32 v38, v248
	v_rcp_f32_e32 v39, v249
	v_rcp_f32_e32 v40, v250
	v_rcp_f32_e32 v41, v251
	v_rcp_f32_e32 v42, v252
	v_rcp_f32_e32 v43, v253
	v_pk_mul_f32 v[28:29], v[28:29], v[36:37]
	v_pk_mul_f32 v[30:31], v[30:31], v[38:39]
	v_pk_mul_f32 v[24:25], v[24:25], v[40:41]
	v_pk_mul_f32 v[26:27], v[26:27], v[42:43]
	v_pk_mul_f32 v[20:21], v[20:21], v[28:29]
	v_pk_mul_f32 v[22:23], v[22:23], v[30:31]
	v_pk_mul_f32 v[24:25], v[16:17], v[24:25]
	v_pk_mul_f32 v[26:27], v[18:19], v[26:27]
	v_cvt_pk_bf16_f32 v16, v20, v21
	v_cvt_pk_bf16_f32 v17, v22, v23
	v_cvt_pk_bf16_f32 v18, v24, v25
	v_cvt_pk_bf16_f32 v19, v26, v27
	global_store_dwordx4 v[34:35], v[16:19], off nt
	s_nop 1
	s_andn2_b64 vcc, exec, s[2:3]
	s_mov_b64 s[2:3], -1
	v_fmamk_f32 v16, v195, 0x3a800000, v171
	v_mul_f32_e32 v17, 0x4b800000, v16
	v_cmp_gt_f32_e64 s[4:5], s40, v16
	s_nop 1
	v_cndmask_b32_e64 v16, v16, v17, s[4:5]
	v_rsq_f32_e32 v18, v16
	v_lshl_add_u64 v[16:17], s[18:19], 0, v[154:155]
	v_lshl_add_u64 v[16:17], v[16:17], 0, v[136:137]
	v_mul_f32_e32 v19, 0x45800000, v18
	v_cndmask_b32_e64 v18, v18, v19, s[4:5]
	v_pk_mul_f32 v[12:13], v[12:13], v[18:19] op_sel_hi:[1,0]
	v_pk_mul_f32 v[14:15], v[14:15], v[18:19] op_sel_hi:[1,0]
	v_pk_mul_f32 v[8:9], v[8:9], v[18:19] op_sel_hi:[1,0]
	v_pk_mul_f32 v[10:11], v[10:11], v[18:19] op_sel_hi:[1,0]
	v_pk_mul_f32 v[4:5], v[4:5], v[18:19] op_sel_hi:[1,0]
	v_pk_mul_f32 v[6:7], v[6:7], v[18:19] op_sel_hi:[1,0]
	v_pk_mul_f32 v[0:1], v[0:1], v[18:19] op_sel_hi:[1,0]
	v_pk_mul_f32 v[2:3], v[2:3], v[18:19] op_sel_hi:[1,0]
	v_pk_mul_f32 v[246:247], v[12:13], v[254:255] op_sel_hi:[1,0]
	v_pk_mul_f32 v[248:249], v[14:15], v[254:255] op_sel_hi:[1,0]
	v_pk_mul_f32 v[250:251], v[8:9], v[254:255] op_sel_hi:[1,0]
	v_pk_mul_f32 v[252:253], v[10:11], v[254:255] op_sel_hi:[1,0]
	v_exp_f32_e32 v246, v246
	v_exp_f32_e32 v247, v247
	v_exp_f32_e32 v248, v248
	v_exp_f32_e32 v249, v249
	v_exp_f32_e32 v250, v250
	v_exp_f32_e32 v251, v251
	v_exp_f32_e32 v252, v252
	v_exp_f32_e32 v253, v253
	v_pk_add_f32 v[246:247], v[246:247], 1.0 op_sel_hi:[1,0]
	v_pk_add_f32 v[248:249], v[248:249], 1.0 op_sel_hi:[1,0]
	v_pk_add_f32 v[250:251], v[250:251], 1.0 op_sel_hi:[1,0]
	v_pk_add_f32 v[252:253], v[252:253], 1.0 op_sel_hi:[1,0]
	v_rcp_f32_e32 v18, v246
	v_rcp_f32_e32 v19, v247
	v_rcp_f32_e32 v20, v248
	v_rcp_f32_e32 v21, v249
	v_rcp_f32_e32 v22, v250
	v_rcp_f32_e32 v23, v251
	v_rcp_f32_e32 v24, v252
	v_rcp_f32_e32 v25, v253
	v_pk_mul_f32 v[12:13], v[12:13], v[18:19]
	v_pk_mul_f32 v[14:15], v[14:15], v[20:21]
	v_pk_mul_f32 v[8:9], v[8:9], v[22:23]
	v_pk_mul_f32 v[10:11], v[10:11], v[24:25]
	v_pk_mul_f32 v[4:5], v[4:5], v[12:13]
	v_pk_mul_f32 v[6:7], v[6:7], v[14:15]
	v_pk_mul_f32 v[8:9], v[0:1], v[8:9]
	v_pk_mul_f32 v[10:11], v[2:3], v[10:11]
	v_cvt_pk_bf16_f32 v0, v4, v5
	v_cvt_pk_bf16_f32 v1, v6, v7
	v_cvt_pk_bf16_f32 v2, v8, v9
	v_cvt_pk_bf16_f32 v3, v10, v11
	global_store_dwordx4 v[16:17], v[0:3], off nt
	s_cbranch_vccnz .LBB0_1623
	s_andn2_b64 vcc, exec, s[0:1]
	s_cbranch_vccnz .LBB0_1622
	s_barrier
	s_branch .LBB0_1622
